# speedup vs baseline: 1.0029x; 1.0029x over previous
; DI int crow(int g, int h) { return (g & 3) + 8 * (g >> 2) + 4 * h; }
; #define MFMA32(a, b, c) __builtin_amdgcn_mfma_f32_32x32x16_bf16((a), (b), (c), 0, 0, 0)
; template <bool GLA, int MODE> ...
;     ...
; #pragma unroll
;         for (int js = 0; js < 4; ++js) {
;             const bf16x8 vb = *(const bf16x8*)(lds + S_VT + (hu * DVH + dv0 + r) * S_TS + (16 * js + 8 * hh) * 2);
;             if (MODE == 0) {
;                 if (js < 2) { const bf16x8 a0 = *(const bf16x8*)(lds + S_ATT + hu * 64 * S_TS + r * S_TS + (16 * js + 8 * hh) * 2); oa[0] = MFMA32(a0, vb, oa[0]); }
;                 { const bf16x8 a1 = *(const bf16x8*)(lds + S_ATT + hu * 64 * S_TS + (32 + r) * S_TS + (16 * js + 8 * hh) * 2); oa[1] = MFMA32(a1, vb, oa[1]); }
;             }
; #pragma unroll
;             for (int kt = 0; kt < KT; ++kt) {
;                 const bf16x8 ka = *(const bf16x8*)(lds + S_KST + (hu * DK + 32 * kt + r) * S_TS + (16 * js + 8 * hh) * 2);
;                 S[kt] = MFMA32(ka, vb, S[kt]);
;             }
;         }
; #pragma unroll
;         for (int kt = 0; kt < KT; ++kt)
; #pragma unroll
;             for (int g = 0; g < 16; ++g) S[kt][g] *= DEC[hu * DK + 32 * kt + crow(g, hh)];
;         __syncthreads();
.Lmy_l1r_join:
	s_waitcnt lgkmcnt(0)
	s_barrier
	ds_read_b128 v[42:45], v86 offset:53248
	ds_read_b128 v[46:49], v86 offset:53280
	ds_read_b128 v[50:53], v85 offset:34816
	ds_read_b128 v[54:57], v85 offset:34848
	s_waitcnt lgkmcnt(1)
	v_mfma_f32_32x32x16_bf16 v[18:33], v[50:53], v[42:45], v[18:33]
	ds_read_b128 v[50:53], v85 offset:39424
	s_add_i32 s7, s7, 64
	v_add_f32_e32 v1, v1, v88
	s_cmp_eq_u32 s4, s6
	s_waitcnt lgkmcnt(0)
	v_mfma_f32_32x32x16_bf16 v[2:17], v[50:53], v[42:45], v[2:17]
	ds_read_b128 v[42:45], v85 offset:39456
	v_mfma_f32_32x32x16_bf16 v[18:33], v[54:57], v[46:49], v[18:33]
	s_waitcnt lgkmcnt(0)
	v_mfma_f32_32x32x16_bf16 v[2:17], v[42:45], v[46:49], v[2:17]
	ds_read_b128 v[42:45], v86 offset:53312
	ds_read_b128 v[46:49], v85 offset:34880
	s_waitcnt lgkmcnt(0)
	v_mfma_f32_32x32x16_bf16 v[18:33], v[46:49], v[42:45], v[18:33]
	ds_read_b128 v[46:49], v85 offset:39488
	s_waitcnt lgkmcnt(0)
	v_mfma_f32_32x32x16_bf16 v[2:17], v[46:49], v[42:45], v[2:17]
	ds_read_b128 v[42:45], v86 offset:53344
	ds_read_b128 v[46:49], v85 offset:34912
	s_waitcnt lgkmcnt(0)
	v_mfma_f32_32x32x16_bf16 v[18:33], v[46:49], v[42:45], v[18:33]
	ds_read_b128 v[46:49], v85 offset:39520
	s_waitcnt lgkmcnt(0)
	v_mfma_f32_32x32x16_bf16 v[2:17], v[46:49], v[42:45], v[2:17]
	ds_read_b128 v[42:45], v87
	ds_read_b128 v[46:49], v87 offset:32
	s_waitcnt lgkmcnt(1)
	s_nop 5
	v_mul_f32_e64 v18, v18, v42
	v_mul_f32_e64 v19, v19, v43
	v_pk_mul_f32 v[20:21], v[20:21], v[44:45]
	ds_read_b128 v[42:45], v87 offset:64
	s_waitcnt lgkmcnt(1)
	v_pk_mul_f32 v[22:23], v[22:23], v[46:47]
	v_pk_mul_f32 v[24:25], v[24:25], v[48:49]
	s_waitcnt lgkmcnt(0)
	v_pk_mul_f32 v[26:27], v[26:27], v[42:43]
	v_pk_mul_f32 v[28:29], v[28:29], v[44:45]
	ds_read_b128 v[42:45], v87 offset:96
	s_waitcnt lgkmcnt(0)
	v_pk_mul_f32 v[30:31], v[30:31], v[42:43]
	v_pk_mul_f32 v[32:33], v[32:33], v[44:45]
	ds_read_b128 v[42:45], v87 offset:128
	s_waitcnt lgkmcnt(0)
	v_pk_mul_f32 v[2:3], v[2:3], v[42:43]
	v_pk_mul_f32 v[4:5], v[4:5], v[44:45]
	ds_read_b128 v[42:45], v87 offset:160
	s_waitcnt lgkmcnt(0)
	v_pk_mul_f32 v[6:7], v[6:7], v[42:43]
	v_pk_mul_f32 v[8:9], v[8:9], v[44:45]
	ds_read_b128 v[42:45], v87 offset:192
	s_waitcnt lgkmcnt(0)
	v_pk_mul_f32 v[10:11], v[10:11], v[42:43]
	v_pk_mul_f32 v[12:13], v[12:13], v[44:45]
	ds_read_b128 v[42:45], v87 offset:224
	s_waitcnt lgkmcnt(0)
	s_barrier
	v_pk_mul_f32 v[14:15], v[14:15], v[42:43]
	v_pk_mul_f32 v[16:17], v[16:17], v[44:45]
	s_cbranch_scc1 .LBB0_1139

; template <bool GLA, int MODE> ...
;     ...
;         if (c + 1 < nch) { int cn = cidx + 1, rn = row0 + 64; asm volatile("" : "+s"(cn)); asm volatile("" : "+s"(rn)); SCAN_LOAD(cn, rn); }
;         if (MODE == 1) {
; #pragma unroll
;         for (int i = 0; i < 4; ++i) *(u32x4*)(lds + S_VT + (tid >> 1) * S_TS + (16 * i + 8 * (tid & 1)) * 2) = vv[i];
.LBB0_1136:
	s_or_b64 exec, exec, s[60:61]
	s_add_i32 s6, s6, 1
	s_cmp_ge_u32 s6, s4
	s_cbranch_scc1 .LBB0_1133
	s_add_i32 s9, s9, 1
	s_add_i32 s8, s8, 64
	s_nop 0
	v_mad_i64_i32 v[38:39], s[8:9], s9, v225, v[60:61]
	global_load_dwordx4 v[34:37], v[38:39], off offset:16
	s_nop 0
	global_load_dwordx4 v[38:41], v[38:39], off
	s_waitcnt vmcnt(5)
	ds_write_b128 v84, v[42:45] offset:53248
	s_waitcnt vmcnt(4)
	ds_write_b128 v84, v[46:49] offset:53280
	s_waitcnt vmcnt(3)
	ds_write_b128 v84, v[50:53] offset:53312
	s_waitcnt vmcnt(2)
	ds_write_b128 v84, v[54:57] offset:53344
	s_branch .Lmy_l1r_join

; DI int crow(int g, int h) { return (g & 3) + 8 * (g >> 2) + 4 * h; }
; #define MFMA32(a, b, c) __builtin_amdgcn_mfma_f32_32x32x16_bf16((a), (b), (c), 0, 0, 0)
; template <bool GLA, int MODE> ...
;     ...
; #pragma unroll
;         for (int js = 0; js < 4; ++js) {
;             const bf16x8 vb = *(const bf16x8*)(lds + S_VT + (hu * DVH + dv0 + r) * S_TS + (16 * js + 8 * hh) * 2);
;             if (MODE == 0) {
;                 if (js < 2) { const bf16x8 a0 = *(const bf16x8*)(lds + S_ATT + hu * 64 * S_TS + r * S_TS + (16 * js + 8 * hh) * 2); oa[0] = MFMA32(a0, vb, oa[0]); }
;                 { const bf16x8 a1 = *(const bf16x8*)(lds + S_ATT + hu * 64 * S_TS + (32 + r) * S_TS + (16 * js + 8 * hh) * 2); oa[1] = MFMA32(a1, vb, oa[1]); }
;             }
; #pragma unroll
;             for (int kt = 0; kt < KT; ++kt) {
;                 const bf16x8 ka = *(const bf16x8*)(lds + S_KST + (hu * DK + 32 * kt + r) * S_TS + (16 * js + 8 * hh) * 2);
;                 S[kt] = MFMA32(ka, vb, S[kt]);
;             }
;         }
; #pragma unroll
;         for (int kt = 0; kt < KT; ++kt)
; #pragma unroll
;             for (int g = 0; g < 16; ++g) S[kt][g] *= DEC[hu * DK + 32 * kt + crow(g, hh)];
;         __syncthreads();
.Lmy_l1g_join:
	s_waitcnt lgkmcnt(0)
	s_barrier
	ds_read_b128 v[82:85], v113 offset:53248
	ds_read_b128 v[86:89], v113 offset:53280
	ds_read_b128 v[90:93], v112 offset:34816
	ds_read_b128 v[94:97], v112 offset:34848
	s_waitcnt lgkmcnt(1)
	v_mfma_f32_32x32x16_bf16 v[50:65], v[90:93], v[82:85], v[50:65]
	ds_read_b128 v[90:93], v112 offset:39424
	s_add_i32 s7, s7, 64
	v_add_f32_e32 v1, v1, v115
	s_cmp_eq_u32 s5, s6
	s_waitcnt lgkmcnt(0)
	v_mfma_f32_32x32x16_bf16 v[34:49], v[90:93], v[82:85], v[34:49]
	ds_read_b128 v[90:93], v112 offset:44032
	s_waitcnt lgkmcnt(0)
	v_mfma_f32_32x32x16_bf16 v[18:33], v[90:93], v[82:85], v[18:33]
	ds_read_b128 v[90:93], v112 offset:48640
	s_waitcnt lgkmcnt(0)
	v_mfma_f32_32x32x16_bf16 v[2:17], v[90:93], v[82:85], v[2:17]
	ds_read_b128 v[82:85], v112 offset:39456
	s_waitcnt lgkmcnt(0)
	v_mfma_f32_32x32x16_bf16 v[34:49], v[82:85], v[86:89], v[34:49]
	ds_read_b128 v[82:85], v112 offset:44064
	s_waitcnt lgkmcnt(0)
	v_mfma_f32_32x32x16_bf16 v[18:33], v[82:85], v[86:89], v[18:33]
	ds_read_b128 v[82:85], v112 offset:48672
	v_mfma_f32_32x32x16_bf16 v[50:65], v[94:97], v[86:89], v[50:65]
	s_waitcnt lgkmcnt(0)
	v_mfma_f32_32x32x16_bf16 v[2:17], v[82:85], v[86:89], v[2:17]
	ds_read_b128 v[82:85], v113 offset:53312
	ds_read_b128 v[86:89], v112 offset:34880
	s_waitcnt lgkmcnt(0)
	v_mfma_f32_32x32x16_bf16 v[50:65], v[86:89], v[82:85], v[50:65]
	ds_read_b128 v[86:89], v112 offset:39488
	s_waitcnt lgkmcnt(0)
	v_mfma_f32_32x32x16_bf16 v[34:49], v[86:89], v[82:85], v[34:49]
	ds_read_b128 v[86:89], v112 offset:44096
	s_waitcnt lgkmcnt(0)
	v_mfma_f32_32x32x16_bf16 v[18:33], v[86:89], v[82:85], v[18:33]
	ds_read_b128 v[86:89], v112 offset:48704
	s_waitcnt lgkmcnt(0)
	v_mfma_f32_32x32x16_bf16 v[2:17], v[86:89], v[82:85], v[2:17]
	ds_read_b128 v[82:85], v113 offset:53344
	ds_read_b128 v[86:89], v112 offset:34912
	s_waitcnt lgkmcnt(0)
	v_mfma_f32_32x32x16_bf16 v[50:65], v[86:89], v[82:85], v[50:65]
	ds_read_b128 v[86:89], v112 offset:39520
	s_waitcnt lgkmcnt(0)
	v_mfma_f32_32x32x16_bf16 v[34:49], v[86:89], v[82:85], v[34:49]
	ds_read_b128 v[86:89], v112 offset:44128
	s_waitcnt lgkmcnt(0)
	v_mfma_f32_32x32x16_bf16 v[18:33], v[86:89], v[82:85], v[18:33]
	ds_read_b128 v[86:89], v112 offset:48736
	s_waitcnt lgkmcnt(0)
	v_mfma_f32_32x32x16_bf16 v[2:17], v[86:89], v[82:85], v[2:17]
	ds_read_b128 v[82:85], v114
	ds_read_b128 v[86:89], v114 offset:32
	s_waitcnt lgkmcnt(1)
	v_mul_f32_e64 v50, v50, v82
	v_mul_f32_e64 v51, v51, v83
	v_pk_mul_f32 v[52:53], v[52:53], v[84:85]
	ds_read_b128 v[82:85], v114 offset:64
	s_waitcnt lgkmcnt(1)
	v_pk_mul_f32 v[54:55], v[54:55], v[86:87]
	v_pk_mul_f32 v[56:57], v[56:57], v[88:89]
	s_waitcnt lgkmcnt(0)
	v_pk_mul_f32 v[58:59], v[58:59], v[82:83]
	v_pk_mul_f32 v[60:61], v[60:61], v[84:85]
	ds_read_b128 v[82:85], v114 offset:96
	s_waitcnt lgkmcnt(0)
	v_pk_mul_f32 v[62:63], v[62:63], v[82:83]
	v_pk_mul_f32 v[64:65], v[64:65], v[84:85]
	ds_read_b128 v[82:85], v114 offset:128
	s_waitcnt lgkmcnt(0)
	v_pk_mul_f32 v[34:35], v[34:35], v[82:83]
	v_pk_mul_f32 v[36:37], v[36:37], v[84:85]
	ds_read_b128 v[82:85], v114 offset:160
	s_waitcnt lgkmcnt(0)
	v_pk_mul_f32 v[38:39], v[38:39], v[82:83]
	v_pk_mul_f32 v[40:41], v[40:41], v[84:85]
	ds_read_b128 v[82:85], v114 offset:192
	s_waitcnt lgkmcnt(0)
	v_pk_mul_f32 v[42:43], v[42:43], v[82:83]
	v_pk_mul_f32 v[44:45], v[44:45], v[84:85]
	ds_read_b128 v[82:85], v114 offset:224
	s_waitcnt lgkmcnt(0)
	v_pk_mul_f32 v[46:47], v[46:47], v[82:83]
	v_pk_mul_f32 v[48:49], v[48:49], v[84:85]
	ds_read_b128 v[82:85], v114 offset:256
	s_waitcnt lgkmcnt(0)
	v_pk_mul_f32 v[18:19], v[18:19], v[82:83]
	v_pk_mul_f32 v[20:21], v[20:21], v[84:85]
	ds_read_b128 v[82:85], v114 offset:288
	s_waitcnt lgkmcnt(0)
	v_pk_mul_f32 v[22:23], v[22:23], v[82:83]
	v_pk_mul_f32 v[24:25], v[24:25], v[84:85]
	ds_read_b128 v[82:85], v114 offset:320
	s_waitcnt lgkmcnt(0)
	v_pk_mul_f32 v[26:27], v[26:27], v[82:83]
	v_pk_mul_f32 v[28:29], v[28:29], v[84:85]
	ds_read_b128 v[82:85], v114 offset:352
	s_waitcnt lgkmcnt(0)
	v_pk_mul_f32 v[30:31], v[30:31], v[82:83]
	v_pk_mul_f32 v[32:33], v[32:33], v[84:85]
	ds_read_b128 v[82:85], v114 offset:384
	s_waitcnt lgkmcnt(0)
	v_pk_mul_f32 v[2:3], v[2:3], v[82:83]
	v_pk_mul_f32 v[4:5], v[4:5], v[84:85]
	ds_read_b128 v[82:85], v114 offset:416
	s_waitcnt lgkmcnt(0)
	v_pk_mul_f32 v[6:7], v[6:7], v[82:83]
	v_pk_mul_f32 v[8:9], v[8:9], v[84:85]
	ds_read_b128 v[82:85], v114 offset:448
	s_waitcnt lgkmcnt(0)
	v_pk_mul_f32 v[10:11], v[10:11], v[82:83]
	v_pk_mul_f32 v[12:13], v[12:13], v[84:85]
	ds_read_b128 v[82:85], v114 offset:480
	s_waitcnt lgkmcnt(0)
	s_barrier
	v_pk_mul_f32 v[14:15], v[14:15], v[82:83]
	v_pk_mul_f32 v[16:17], v[16:17], v[84:85]
	s_cbranch_scc1 .LBB0_1148

; template <bool GLA, int MODE> ...
;     ...
;         if (c + 1 < nch) { int cn = cidx + 1, rn = row0 + 64; asm volatile("" : "+s"(cn)); asm volatile("" : "+s"(rn)); SCAN_LOAD(cn, rn); }
;         if (MODE == 1) {
; #pragma unroll
;         for (int i = 0; i < 4; ++i) *(u32x4*)(lds + S_VT + (tid >> 1) * S_TS + (16 * i + 8 * (tid & 1)) * 2) = vv[i];
.LBB0_1146:
	s_or_b64 exec, exec, s[56:57]
	s_add_i32 s6, s6, 1
	s_cmp_ge_u32 s6, s5
	s_cbranch_scc1 .LBB0_1143
	s_add_i32 s10, s9, 1
	s_add_i32 s8, s8, 64
	s_ashr_i32 s11, s10, 31
	v_mad_i64_i32 v[70:71], s[8:9], s10, v225, v[102:103]
	s_lshl_b64 s[8:9], s[10:11], 16
	s_nop 0
	v_lshl_add_u64 v[78:79], v[106:107], 0, s[8:9]
	global_load_dwordx4 v[66:69], v[70:71], off offset:16
	s_nop 0
	global_load_dwordx4 v[70:73], v[70:71], off
	s_nop 0
	global_load_dwordx4 v[74:77], v[78:79], off
	s_nop 0
	global_load_dwordx4 v[78:81], v[78:79], off offset:16
	s_waitcnt vmcnt(7)
	ds_write_b128 v111, v[82:85] offset:53248
	s_waitcnt vmcnt(6)
	ds_write_b128 v111, v[86:89] offset:53280
	s_waitcnt vmcnt(5)
	ds_write_b128 v111, v[90:93] offset:53312
	s_waitcnt vmcnt(4)
	ds_write_b128 v111, v[94:97] offset:53344
	s_branch .Lmy_l1g_join
